# GPRIO-young: NOPRIO plus one static s_setprio 1 for waves 4-7 at every GEMM tile-loop entry (reset at phase end)
# baseline (speedup 1.0000x reference)
; __global__ void __launch_bounds__(512) mega(Params p_arg) {
;     ...
;     for (int ph = 1; ph < N_PHASES; ++ph) {
;         for (int rep = 0; rep < (((ph - 1) % PH_PER_GROUP == REPEAT_Q) ? 2 : 1); ++rep) {
;         if ((ph - 1) % PH_PER_GROUP == 0 && ph > 1) continue;
.LBB0_174:
	s_setprio 0
	s_add_i32 s57, s57, 1
	s_cmp_eq_u32 s57, 23
	s_cbranch_scc0 .LBB0_175
	s_getpc_b64 s[98:99]

; template <class Epi, class Sched>
; __device__ __forceinline__ void gemm_phase(PG8_LAS unsigned char* lds, const Gemm g, const Sched& S, const Epi& E, int tid_in) {
;     ...
;     Unit cur, nxt; int ui = 0;
;     if (!S.next(0, cur)) return;
.LBB0_255:
	v_readfirstlane_b32 s100, v240
	s_nop 3
	s_lshr_b32 s100, s100, 6
	s_cmp_gt_u32 s100, 3
	s_cbranch_scc0 .Lgprio_255
	s_setprio 1

; #define PG8_STAGE(bufoff, gbase, voff) do { _Pragma("unroll") for (int _i = 0; _i < 2; ++_i) \
;         __builtin_amdgcn_global_load_lds((const unsigned*)((const char*)(gbase) + (voff)[_i]), (PG8_LAS unsigned*)(lds + (bufoff) + ldsw + _i * 8192), 16, 0, 0); } while (0)
; #define PG8_WAIT_V(n) asm volatile("s_waitcnt vmcnt(" #n ")" ::: "memory")
; #define PG8_BAR __builtin_amdgcn_s_barrier()
; template <class Epi, class Sched>
; __device__ __forceinline__ void gemm_phase(PG8_LAS unsigned char* lds, const Gemm g, const Sched& S, const Epi& E, int tid_in) {
;     ...
;     const int tid = tid_, wid = __builtin_amdgcn_readfirstlane(tid >> 6), lane = tid & 63, wr = wid >> 2, wc = wid & 3, fr = lane & 15, fq = lane >> 4;
;     const int K = g.K, nt = K / BK;
;     unsigned voffA[2], voffB[2];
; #pragma unroll
;     for (int i = 0; i < 2; ++i) { int R, C; stage_rc(tid * 16 + i * 8192, R, C); const int Rb = Epi::PERM ? ((R & ~31) + perm32(R & 31)) : R;
;         voffA[i] = (unsigned)(R * K + C) * 2u; voffB[i] = (unsigned)(Rb * K + C) * 2u; }
;     const size_t kstep = (size_t)(BK * 2);
;     const size_t hstep = (size_t)HALF * K * 2;
;     const size_t tstep = 2 * hstep;
;     const unsigned ldsw = (unsigned)wid * 1024u;
;     const int aoff = lds_byte(wr * 64 + fr, fq * 8), boff = lds_byte(wc * 32 + fr, fq * 8);
;     ...
;     Unit cur, nxt; int ui = 0;
;     if (!S.next(0, cur)) return;
;     f32x4 acc[2][2][4][2];
; #pragma unroll
;     for (int a = 0; a < 2; ++a)
; #pragma unroll
;         for (int b = 0; b < 2; ++b)
; #pragma unroll
;             for (int m = 0; m < 4; ++m)
; #pragma unroll
;                 for (int n = 0; n < 2; ++n) acc[a][b][m][n] = (f32x4){0.f, 0.f, 0.f, 0.f};
;     bf16x8 At[4][2], B0[2][2], B1[2][2];
;     const char* cA = (const char*)g.A + (size_t)cur.pm * tstep; const char* cB = (const char*)g.Bt + (size_t)cur.pn * tstep;
;     S.a_ready(cur);
;     PG8_STAGE(PG8_SB(0, 0), cB, voffB); PG8_STAGE(PG8_SA(0, 0), cA, voffA); PG8_STAGE(PG8_SB(0, 1), cB + hstep, voffB); PG8_STAGE(PG8_SA(0, 1), cA + hstep, voffA);
;     if (wr == 1) PG8_BAR;
;     PG8_WAIT_V(4); PG8_BAR;
;     PG8_STAGE(PG8_SB(1, 0), cB + kstep, voffB); PG8_STAGE(PG8_SA(1, 0), cA + kstep, voffA); PG8_STAGE(PG8_SB(1, 1), cB + hstep + kstep, voffB);
.LBB0_379:
	s_andn2_b64 vcc, exec, s[2:3]
	s_cbranch_vccnz .LBB0_415
	v_readfirstlane_b32 s100, v240
	s_nop 3
	s_lshr_b32 s100, s100, 6
	s_cmp_gt_u32 s100, 3
	s_cbranch_scc0 .Lgprio_380
	s_setprio 1
.Lgprio_380:
	v_ashrrev_i32_e32 v1, 31, v8
	v_lshrrev_b32_e32 v1, 26, v1
	v_add_u32_e32 v1, v8, v1
	v_ashrrev_i32_e32 v9, 6, v1
	v_bfe_i32 v1, v8, 27, 1
	v_lshlrev_b32_e32 v0, 4, v8
	v_lshrrev_b32_e32 v1, 22, v1
	v_add_u32_e32 v1, v0, v1
	v_and_b32_e32 v1, 0xfffffc00, v1
	v_sub_u32_e32 v1, v0, v1
	v_lshrrev_b32_e32 v2, 4, v1
	v_bitop3_b32 v1, v2, v1, 32 bitop3:0x6c
	v_ashrrev_i32_e32 v3, 31, v1
	v_lshrrev_b32_e32 v3, 26, v3
	v_add_u32_e32 v3, v1, v3
	v_lshlrev_b32_e32 v2, 3, v9
	v_ashrrev_i32_e32 v10, 6, v3
	v_and_b32_e32 v3, 0xc0, v3
	v_and_b32_e32 v2, -16, v2
	v_sub_u32_e32 v1, v1, v3
	v_mov_b32_e32 v6, 1
	v_add_u32_e32 v2, v10, v2
	v_ashrrev_i16_sdwa v1, v6, sext(v1) dst_sel:DWORD dst_unused:UNUSED_PAD src0_sel:DWORD src1_sel:BYTE_0
	v_lshlrev_b32_e32 v4, 5, v9
	v_bfe_i32 v11, v1, 0, 16
	v_lshlrev_b32_e32 v1, 1, v2
	v_lshrrev_b32_e32 v3, 2, v2
	v_and_b32_e32 v5, 3, v10
	s_mov_b32 s1, 0x1fffe0
	v_and_b32_e32 v4, 32, v4
	v_and_b32_e32 v1, 24, v1
	v_and_b32_e32 v3, 4, v3
	v_and_or_b32 v5, v2, s1, v5
	v_or3_b32 v1, v5, v3, v1
	v_add_lshl_u32 v3, v4, v11, 1
	v_add_u32_e32 v0, 0x2000, v0
	v_lshl_add_u32 v202, v1, 11, v3
	v_ashrrev_i32_e32 v1, 31, v0
	v_lshrrev_b32_e32 v1, 22, v1
	v_add_u32_e32 v1, v0, v1
	v_ashrrev_i32_e32 v12, 10, v1
	v_mul_i32_i24_e32 v1, 0x400, v12
	v_sub_u32_e32 v0, v0, v1
	v_lshrrev_b32_e32 v1, 4, v0
	v_bitop3_b32 v0, v1, v0, 32 bitop3:0x6c
	v_lshl_add_u32 v200, v2, 11, v3
	v_ashrrev_i32_e32 v2, 31, v0
	v_lshrrev_b32_e32 v2, 26, v2
	s_waitcnt lgkmcnt(0)
	s_add_u32 s63, s94, 0x3900000
	v_lshlrev_b32_e32 v1, 3, v12
	v_add_u32_e32 v2, v0, v2
	s_addc_u32 s64, s95, 0
	v_and_b32_e32 v1, -16, v1
	v_ashrrev_i32_e32 v13, 6, v2
	s_add_u32 s65, s94, 0xb80000
	v_add_u32_e32 v1, v13, v1
	v_and_b32_e32 v4, 3, v13
	s_mov_b64 s[96:97], s[68:69]
	s_addc_u32 s69, s95, 0
	s_ashr_i32 s2, s62, 6
	v_and_b32_e32 v2, 0xc0, v2
	v_and_or_b32 v4, v1, s1, v4
	s_ashr_i32 s1, s0, 31
	s_ashr_i32 s25, s24, 31
	v_sub_u32_e32 v0, v0, v2
	s_ashr_i32 s3, s62, 8
	s_lshl_b32 s72, s2, 10
	s_lshl_b64 s[4:5], s[0:1], 19
	s_lshl_b64 s[6:7], s[24:25], 19
	v_ashrrev_i16_sdwa v0, v6, sext(v0) dst_sel:DWORD dst_unused:UNUSED_PAD src0_sel:DWORD src1_sel:BYTE_0
	s_add_u32 s28, s65, s6
	v_lshlrev_b32_e32 v3, 5, v12
	v_bfe_i32 v14, v0, 0, 16
	v_lshlrev_b32_e32 v0, 1, v1
	v_lshrrev_b32_e32 v2, 2, v1
	s_addc_u32 s29, s69, s7
	s_add_i32 s73, s72, 0
	v_and_b32_e32 v3, 32, v3
	v_and_b32_e32 v0, 24, v0
	v_and_b32_e32 v2, 4, v2
	s_add_i32 m0, s73, 0x10000
	v_or3_b32 v0, v4, v2, v0
	v_add_lshl_u32 v2, v3, v14, 1
	global_load_lds_dwordx4 v202, s[28:29]
	s_add_i32 m0, s73, 0x12000
	s_mov_b32 s84, s26
	v_lshl_add_u32 v206, v0, 11, v2
	s_add_u32 s26, s63, s4
	s_mov_b32 s46, s76
	global_load_lds_dwordx4 v206, s[28:29]
	s_addc_u32 s27, s64, s5
	s_mov_b32 m0, s73
	s_add_i32 s76, s73, 0x2000
	v_lshl_add_u32 v204, v1, 11, v2
	global_load_lds_dwordx4 v200, s[26:27]
	s_mov_b32 m0, s76
	s_add_u32 s4, s28, 0x40000
	global_load_lds_dwordx4 v204, s[26:27]
	s_addc_u32 s5, s29, 0
	s_add_i32 m0, s73, 0x14000
	v_writelane_b32 v255, s80, 36
	global_load_lds_dwordx4 v202, s[4:5]
	s_add_i32 m0, s73, 0x16000
	v_writelane_b32 v255, s81, 37
	global_load_lds_dwordx4 v206, s[4:5]
	s_add_u32 s4, s26, 0x40000
	s_addc_u32 s5, s27, 0
	s_add_i32 s77, s73, 0x4000
	s_mov_b32 m0, s77
	s_add_i32 s78, s73, 0x6000
	global_load_lds_dwordx4 v200, s[4:5]
	s_mov_b32 m0, s78
	v_writelane_b32 v255, s82, 38
	global_load_lds_dwordx4 v204, s[4:5]
	v_mov_b32_e32 v203, v193
	v_mov_b32_e32 v207, v193
	v_mov_b32_e32 v201, v193
	v_mov_b32_e32 v205, v193
	v_writelane_b32 v255, s83, 39
	s_mov_b64 s[42:43], s[38:39]
	v_lshl_add_u64 v[6:7], s[28:29], 0, v[202:203]
	v_lshl_add_u64 v[4:5], s[28:29], 0, v[206:207]
	v_lshl_add_u64 v[2:3], s[26:27], 0, v[200:201]
	s_cmp_lg_u32 s3, 1
	v_lshl_add_u64 v[0:1], s[26:27], 0, v[204:205]
	s_movk_i32 s41, 0x141
	s_cbranch_scc1 .LBB0_382
	s_barrier
